# adds: MLA pass 1 walks KV tiles in descending order (L2 reuse across CUs sharing a head)
# speedup vs baseline: 1.0201x; 1.0097x over previous
.LBB0_145:
	s_xor_b64 s[30:31], s[18:19], -1
	s_and_b64 s[18:19], s[18:19], exec
	s_cselect_b32 s2, s84, s48
	s_cmp_lg_u64 s[30:31], 0
	s_cselect_b32 s100, 0xffffe000, s96
	s_cselect_b32 s101, -1, 0
	s_movk_i32 s8, 0xd0
	s_or_b32 s18, s34, s2
	s_ashr_i32 s19, s8, 31
	s_add_u32 s36, s0, s8
	s_addc_u32 s37, s1, s19
	s_load_dwordx2 s[36:37], s[36:37], 0x0
	s_mul_hi_u32 s19, s18, 0xa00
	s_mul_i32 s33, s35, 0xa00
	s_mul_i32 s8, s18, 0xa00
	s_add_i32 s19, s19, s33
	s_waitcnt lgkmcnt(0)
	s_add_u32 s8, s36, s8
	s_addc_u32 s19, s37, s19
	s_add_u32 s56, s8, s26
	s_movk_i32 s8, 0xd0
	s_addc_u32 s57, s19, s27
	s_ashr_i32 s19, s8, 31
	s_add_u32 s36, s0, s8
	s_addc_u32 s37, s1, s19
	s_load_dwordx2 s[42:43], s[36:37], 0x0
	v_lshl_add_u64 v[0:1], s[56:57], 0, v[170:171]
	v_lshl_add_u64 v[0:1], v[172:173], 1, v[0:1]
	s_mov_b64 s[56:57], 0x1a800000
	v_lshl_add_u64 v[24:25], v[0:1], 0, s[56:57]
	s_waitcnt lgkmcnt(0)
	s_add_u32 s8, s42, s9
	s_addc_u32 s19, s43, s49
	s_add_u32 s8, s8, s22
	s_addc_u32 s19, s19, s23
	s_add_u32 s36, s8, 0x32800000
	s_movk_i32 s8, 0xd0
	s_addc_u32 s37, s19, 0
	s_ashr_i32 s19, s8, 31
	s_add_u32 s74, s0, s8
	s_addc_u32 s75, s1, s19
	s_movk_i32 s8, 0xd0
	s_load_dwordx2 s[74:75], s[74:75], 0x0
	s_ashr_i32 s19, s8, 31
	s_add_u32 s76, s0, s8
	s_addc_u32 s77, s1, s19
	s_mov_b32 s19, 0x1a800000
	v_add_co_u32_e32 v2, vcc, s19, v0
	s_mov_b32 s8, 16
	s_nop 0
	v_addc_co_u32_e32 v3, vcc, 0, v1, vcc
	s_load_dwordx2 s[78:79], s[76:77], 0x0
	global_load_dwordx4 v[16:19], v[2:3], off
	global_load_dwordx4 v[20:23], v[24:25], off offset:32
	global_load_dwordx4 v[28:31], v[24:25], off offset:64
	global_load_dwordx4 v[32:35], v[24:25], off offset:96
	global_load_dwordx4 v[36:39], v[24:25], off offset:128
	global_load_dwordx4 v[4:7], v[24:25], off offset:352
	global_load_dwordx4 v[68:71], v[24:25], off offset:224
	global_load_dwordx4 v[12:15], v[24:25], off offset:256
	global_load_dwordx4 v[0:3], v[24:25], off offset:288
	global_load_dwordx4 v[8:11], v[24:25], off offset:320
	global_load_dwordx4 v[72:75], v[24:25], off offset:160
	global_load_dwordx4 v[76:79], v[24:25], off offset:192
	s_ashr_i32 s33, s8, 31
	s_add_u32 s76, s0, s8
	s_addc_u32 s77, s1, s33
	s_load_dwordx2 s[76:77], s[76:77], 0x0
	v_add_u32_e32 v26, s18, v167
	v_ashrrev_i32_e32 v27, 31, v26
	global_load_dwordx4 v[80:83], v[174:175], off offset:16
	global_load_dwordx4 v[84:87], v[174:175], off
	s_waitcnt lgkmcnt(0)
	s_add_u32 s8, s74, s20
	v_lshl_add_u64 v[24:25], v[26:27], 2, s[76:77]
	global_load_dword v27, v[24:25], off
	s_addc_u32 s33, s75, s21
	s_mov_b32 s19, s35
	s_mov_b32 s57, 2
	s_add_u32 vcc_lo, s8, 0x3e800000
	s_mov_b32 s8, 0
	s_addc_u32 vcc_hi, s33, 0
	s_waitcnt vmcnt(8)
	v_lshlrev_b32_e32 v24, 16, v68
	v_lshlrev_b32_e32 v102, 16, v20
	v_and_b32_e32 v104, 0xffff0000, v20
	v_and_b32_e32 v90, 0xffff0000, v16
	v_lshlrev_b32_e32 v88, 16, v16
	v_lshlrev_b32_e32 v89, 16, v17
	v_and_b32_e32 v91, 0xffff0000, v17
	v_mul_f32_e32 v17, v90, v90
	v_fmac_f32_e32 v17, v88, v88
	v_fmac_f32_e32 v17, v89, v89
	v_lshlrev_b32_e32 v92, 16, v18
	v_fmac_f32_e32 v17, v91, v91
	v_and_b32_e32 v94, 0xffff0000, v18
	v_fmac_f32_e32 v17, v92, v92
	v_lshlrev_b32_e32 v93, 16, v19
	v_fmac_f32_e32 v17, v94, v94
	v_and_b32_e32 v95, 0xffff0000, v19
	v_fmac_f32_e32 v17, v93, v93
	v_fmac_f32_e32 v17, v95, v95
	v_fmac_f32_e32 v17, v102, v102
	v_lshlrev_b32_e32 v103, 16, v21
	v_fmac_f32_e32 v17, v104, v104
	v_and_b32_e32 v105, 0xffff0000, v21
	v_fmac_f32_e32 v17, v103, v103
	v_lshlrev_b32_e32 v106, 16, v22
	v_fmac_f32_e32 v17, v105, v105
	v_and_b32_e32 v108, 0xffff0000, v22
	v_fmac_f32_e32 v17, v106, v106
	v_lshlrev_b32_e32 v107, 16, v23
	v_fmac_f32_e32 v17, v108, v108
	v_and_b32_e32 v109, 0xffff0000, v23
	v_fmac_f32_e32 v17, v107, v107
	v_lshlrev_b32_e32 v66, 16, v28
	v_fmac_f32_e32 v17, v109, v109
	v_and_b32_e32 v64, 0xffff0000, v28
	v_fmac_f32_e32 v17, v66, v66
	v_lshlrev_b32_e32 v67, 16, v29
	v_fmac_f32_e32 v17, v64, v64
	v_and_b32_e32 v65, 0xffff0000, v29
	v_fmac_f32_e32 v17, v67, v67
	v_lshlrev_b32_e32 v62, 16, v30
	v_fmac_f32_e32 v17, v65, v65
	v_and_b32_e32 v60, 0xffff0000, v30
	v_fmac_f32_e32 v17, v62, v62
	v_lshlrev_b32_e32 v63, 16, v31
	v_fmac_f32_e32 v17, v60, v60
	v_and_b32_e32 v61, 0xffff0000, v31
	v_fmac_f32_e32 v17, v63, v63
	v_lshlrev_b32_e32 v58, 16, v32
	v_fmac_f32_e32 v17, v61, v61
	v_and_b32_e32 v56, 0xffff0000, v32
	v_fmac_f32_e32 v17, v58, v58
	v_lshlrev_b32_e32 v59, 16, v33
	v_fmac_f32_e32 v17, v56, v56
	v_and_b32_e32 v57, 0xffff0000, v33
	v_fmac_f32_e32 v17, v59, v59
	v_lshlrev_b32_e32 v54, 16, v34
	v_fmac_f32_e32 v17, v57, v57
	v_and_b32_e32 v52, 0xffff0000, v34
	v_fmac_f32_e32 v17, v54, v54
	v_lshlrev_b32_e32 v55, 16, v35
	v_fmac_f32_e32 v17, v52, v52
	v_and_b32_e32 v53, 0xffff0000, v35
	v_fmac_f32_e32 v17, v55, v55
	v_lshlrev_b32_e32 v50, 16, v36
	v_fmac_f32_e32 v17, v53, v53
	v_and_b32_e32 v48, 0xffff0000, v36
	v_fmac_f32_e32 v17, v50, v50
	v_lshlrev_b32_e32 v51, 16, v37
	v_fmac_f32_e32 v17, v48, v48
	v_and_b32_e32 v49, 0xffff0000, v37
	v_fmac_f32_e32 v17, v51, v51
	v_lshlrev_b32_e32 v46, 16, v38
	v_fmac_f32_e32 v17, v49, v49
	v_and_b32_e32 v44, 0xffff0000, v38
	v_fmac_f32_e32 v17, v46, v46
	v_fmac_f32_e32 v17, v44, v44
	v_lshlrev_b32_e32 v47, 16, v39
	v_fmac_f32_e32 v17, v47, v47
	v_and_b32_e32 v45, 0xffff0000, v39
	v_fmac_f32_e32 v17, v45, v45
	s_waitcnt vmcnt(4)
	v_lshlrev_b32_e32 v42, 16, v72
	v_fmac_f32_e32 v17, v42, v42
	v_and_b32_e32 v40, 0xffff0000, v72
	v_fmac_f32_e32 v17, v40, v40
	v_lshlrev_b32_e32 v43, 16, v73
	v_fmac_f32_e32 v17, v43, v43
	v_and_b32_e32 v41, 0xffff0000, v73
	v_fmac_f32_e32 v17, v41, v41
	v_lshlrev_b32_e32 v38, 16, v74
	v_fmac_f32_e32 v17, v38, v38
	v_and_b32_e32 v36, 0xffff0000, v74
	v_fmac_f32_e32 v17, v36, v36
	v_lshlrev_b32_e32 v39, 16, v75
	v_fmac_f32_e32 v17, v39, v39
	v_and_b32_e32 v37, 0xffff0000, v75
	v_fmac_f32_e32 v17, v37, v37
	s_waitcnt vmcnt(3)
	v_lshlrev_b32_e32 v34, 16, v76
	v_fmac_f32_e32 v17, v34, v34
	v_and_b32_e32 v32, 0xffff0000, v76
	v_fmac_f32_e32 v17, v32, v32
	v_lshlrev_b32_e32 v35, 16, v77
	v_fmac_f32_e32 v17, v35, v35
	v_and_b32_e32 v33, 0xffff0000, v77
	v_fmac_f32_e32 v17, v33, v33
	v_lshlrev_b32_e32 v30, 16, v78
	v_fmac_f32_e32 v17, v30, v30
	v_and_b32_e32 v28, 0xffff0000, v78
	v_fmac_f32_e32 v17, v28, v28
	v_lshlrev_b32_e32 v31, 16, v79
	v_fmac_f32_e32 v17, v31, v31
	v_and_b32_e32 v29, 0xffff0000, v79
	v_fmac_f32_e32 v17, v29, v29
	v_fmac_f32_e32 v17, v24, v24
	v_and_b32_e32 v22, 0xffff0000, v68
	v_fmac_f32_e32 v17, v22, v22
	v_lshlrev_b32_e32 v25, 16, v69
	v_fmac_f32_e32 v17, v25, v25
	v_and_b32_e32 v23, 0xffff0000, v69
	v_fmac_f32_e32 v17, v23, v23
	v_lshlrev_b32_e32 v16, 16, v70
	v_fmac_f32_e32 v17, v16, v16
	v_and_b32_e32 v18, 0xffff0000, v70
	v_and_b32_e32 v21, 0xffff0000, v71
	v_lshlrev_b32_e32 v20, 16, v71
	v_fmac_f32_e32 v17, v18, v18
	v_pk_mul_f32 v[68:69], v[20:21], v[20:21]
	s_waitcnt vmcnt(1)
	v_mov_b32_e32 v70, v84
	v_add_f32_e32 v17, v17, v68
	v_add_f32_e32 v17, v17, v69
	v_mov_b32_e32 v19, v17
	s_nop 1
	v_permlane32_swap_b32_e32 v17, v19
	v_add_f32_e32 v17, v17, v19
	v_fmamk_f32 v17, v17, 0x3c000000, v253
	v_rsq_f32_e32 v17, v17
	v_mov_b32_e32 v71, v86
	v_mov_b32_e32 v74, v80
	v_mov_b32_e32 v75, v82
	v_mul_f32_e32 v26, 0x3d93cd3a, v17
	s_waitcnt vmcnt(0)
	v_pk_mul_f32 v[68:69], v[26:27], v[88:89] op_sel_hi:[0,1]
	v_pk_mul_f32 v[72:73], v[26:27], v[92:93] op_sel_hi:[0,1]
	v_pk_mul_f32 v[68:69], v[70:71], v[68:69]
	v_pk_mul_f32 v[70:71], v[26:27], v[90:91] op_sel_hi:[0,1]
	v_mov_b32_e32 v86, v85
	v_pk_mul_f32 v[72:73], v[74:75], v[72:73]
	v_pk_mul_f32 v[74:75], v[26:27], v[94:95] op_sel_hi:[0,1]
	v_mov_b32_e32 v82, v81
	v_pk_mul_f32 v[70:71], v[86:87], v[70:71]
	v_pk_mul_f32 v[74:75], v[82:83], v[74:75]
	v_bfe_u32 v76, v71, 16, 1
	v_bfe_u32 v17, v75, 16, 1
	v_bfe_u32 v19, v74, 16, 1
	v_bfe_u32 v77, v70, 16, 1
	v_add3_u32 v70, v70, v77, s64
	v_add3_u32 v71, v71, v76, s64
	v_add3_u32 v19, v74, v19, s64
	v_add3_u32 v17, v75, v17, s64
	v_bfe_u32 v74, v68, 16, 1
	v_bfe_u32 v75, v69, 16, 1
	v_bfe_u32 v76, v72, 16, 1
	v_bfe_u32 v77, v73, 16, 1
	v_add3_u32 v73, v73, v77, s64
	v_add3_u32 v72, v72, v76, s64
	v_add3_u32 v69, v69, v75, s64
	v_add3_u32 v68, v68, v74, s64
	v_lshrrev_b32_e32 v68, 16, v68
	v_lshrrev_b32_e32 v69, 16, v69
	v_lshrrev_b32_e32 v72, 16, v72
	v_lshrrev_b32_e32 v73, 16, v73
	v_and_or_b32 v101, v17, s3, v73
	v_and_or_b32 v100, v19, s3, v72
	v_and_or_b32 v99, v71, s3, v69
	v_and_or_b32 v98, v70, s3, v68
	global_load_dwordx4 v[68:71], v[174:175], off offset:80
	global_load_dwordx4 v[72:75], v[174:175], off offset:64
	v_pk_mul_f32 v[76:77], v[26:27], v[102:103] op_sel_hi:[0,1]
	s_waitcnt vmcnt(0)
	v_mov_b32_e32 v78, v72
	v_mov_b32_e32 v79, v74
	v_pk_mul_f32 v[76:77], v[78:79], v[76:77]
	v_pk_mul_f32 v[78:79], v[26:27], v[104:105] op_sel_hi:[0,1]
	v_mov_b32_e32 v74, v73
	v_pk_mul_f32 v[72:73], v[74:75], v[78:79]
	v_pk_mul_f32 v[74:75], v[26:27], v[106:107] op_sel_hi:[0,1]
	v_mov_b32_e32 v78, v68
	v_mov_b32_e32 v79, v70
	v_pk_mul_f32 v[74:75], v[78:79], v[74:75]
	v_pk_mul_f32 v[78:79], v[26:27], v[108:109] op_sel_hi:[0,1]
	v_mov_b32_e32 v70, v69
	v_pk_mul_f32 v[68:69], v[70:71], v[78:79]
	v_bfe_u32 v70, v73, 16, 1
	v_bfe_u32 v17, v69, 16, 1
	v_bfe_u32 v19, v68, 16, 1
	v_bfe_u32 v71, v72, 16, 1
	v_add3_u32 v71, v72, v71, s64
	v_add3_u32 v70, v73, v70, s64
	v_add3_u32 v19, v68, v19, s64
	v_add3_u32 v17, v69, v17, s64
	v_bfe_u32 v68, v76, 16, 1
	v_bfe_u32 v69, v77, 16, 1
	v_bfe_u32 v72, v74, 16, 1
	v_bfe_u32 v73, v75, 16, 1
	v_add3_u32 v73, v75, v73, s64
	v_add3_u32 v72, v74, v72, s64
	v_add3_u32 v69, v77, v69, s64
	v_add3_u32 v68, v76, v68, s64
	v_lshrrev_b32_e32 v68, 16, v68
	v_lshrrev_b32_e32 v69, 16, v69
	v_lshrrev_b32_e32 v72, 16, v72
	v_lshrrev_b32_e32 v73, 16, v73
	v_and_or_b32 v105, v17, s3, v73
	v_and_or_b32 v104, v19, s3, v72
	v_and_or_b32 v103, v70, s3, v69
	v_and_or_b32 v102, v71, s3, v68
	global_load_dwordx4 v[68:71], v[174:175], off offset:144
	global_load_dwordx4 v[72:75], v[174:175], off offset:128
	v_pk_mul_f32 v[64:65], v[26:27], v[64:65] op_sel_hi:[0,1]
	v_pk_mul_f32 v[60:61], v[26:27], v[60:61] op_sel_hi:[0,1]
	v_pk_mul_f32 v[66:67], v[26:27], v[66:67] op_sel_hi:[0,1]
	v_pk_mul_f32 v[62:63], v[26:27], v[62:63] op_sel_hi:[0,1]
	s_waitcnt vmcnt(0)
	v_mov_b32_e32 v77, v74
	v_mov_b32_e32 v74, v73
	v_mov_b32_e32 v73, v70
	v_mov_b32_e32 v70, v69
	v_mov_b32_e32 v76, v72
	v_pk_mul_f32 v[64:65], v[74:75], v[64:65]
	v_mov_b32_e32 v72, v68
	v_pk_mul_f32 v[60:61], v[70:71], v[60:61]
	v_pk_mul_f32 v[66:67], v[76:77], v[66:67]
	v_pk_mul_f32 v[62:63], v[72:73], v[62:63]
	v_bfe_u32 v17, v61, 16, 1
	v_bfe_u32 v19, v60, 16, 1
	v_bfe_u32 v68, v65, 16, 1
	v_bfe_u32 v69, v64, 16, 1
	v_add3_u32 v64, v64, v69, s64
	v_add3_u32 v65, v65, v68, s64
	v_add3_u32 v19, v60, v19, s64
	v_add3_u32 v17, v61, v17, s64
	v_bfe_u32 v60, v66, 16, 1
	v_bfe_u32 v61, v67, 16, 1
	v_bfe_u32 v68, v62, 16, 1
	v_bfe_u32 v69, v63, 16, 1
	v_add3_u32 v63, v63, v69, s64
	v_add3_u32 v62, v62, v68, s64
	v_add3_u32 v61, v67, v61, s64
	v_add3_u32 v60, v66, v60, s64
	v_lshrrev_b32_e32 v60, 16, v60
	v_lshrrev_b32_e32 v61, 16, v61
	v_lshrrev_b32_e32 v62, 16, v62
	v_lshrrev_b32_e32 v63, 16, v63
	v_and_or_b32 v109, v17, s3, v63
	v_and_or_b32 v108, v19, s3, v62
	v_and_or_b32 v107, v65, s3, v61
	v_and_or_b32 v106, v64, s3, v60
	global_load_dwordx4 v[60:63], v[174:175], off offset:208
	global_load_dwordx4 v[64:67], v[174:175], off offset:192
	v_pk_mul_f32 v[56:57], v[26:27], v[56:57] op_sel_hi:[0,1]
	v_pk_mul_f32 v[52:53], v[26:27], v[52:53] op_sel_hi:[0,1]
	v_pk_mul_f32 v[58:59], v[26:27], v[58:59] op_sel_hi:[0,1]
	v_pk_mul_f32 v[54:55], v[26:27], v[54:55] op_sel_hi:[0,1]
	s_waitcnt vmcnt(0)
	v_mov_b32_e32 v69, v66
	v_mov_b32_e32 v66, v65
	v_mov_b32_e32 v65, v62
	v_mov_b32_e32 v62, v61
	v_mov_b32_e32 v68, v64
	v_pk_mul_f32 v[56:57], v[66:67], v[56:57]
	v_mov_b32_e32 v64, v60
	v_pk_mul_f32 v[52:53], v[62:63], v[52:53]
	v_pk_mul_f32 v[58:59], v[68:69], v[58:59]
	v_pk_mul_f32 v[54:55], v[64:65], v[54:55]
	v_bfe_u32 v17, v53, 16, 1
	v_bfe_u32 v19, v52, 16, 1
	v_bfe_u32 v60, v57, 16, 1
	v_bfe_u32 v61, v56, 16, 1
	v_add3_u32 v56, v56, v61, s64
	v_add3_u32 v57, v57, v60, s64
	v_add3_u32 v19, v52, v19, s64
	v_add3_u32 v17, v53, v17, s64
	v_bfe_u32 v52, v58, 16, 1
	v_bfe_u32 v53, v59, 16, 1
	v_bfe_u32 v60, v54, 16, 1
	v_bfe_u32 v61, v55, 16, 1
	v_add3_u32 v55, v55, v61, s64
	v_add3_u32 v54, v54, v60, s64
	v_add3_u32 v53, v59, v53, s64
	v_add3_u32 v52, v58, v52, s64
	v_lshrrev_b32_e32 v52, 16, v52
	v_lshrrev_b32_e32 v53, 16, v53
	v_lshrrev_b32_e32 v54, 16, v54
	v_lshrrev_b32_e32 v55, 16, v55
	v_and_or_b32 v113, v17, s3, v55
	v_and_or_b32 v112, v19, s3, v54
	v_and_or_b32 v111, v57, s3, v53
	v_and_or_b32 v110, v56, s3, v52
	global_load_dwordx4 v[52:55], v[174:175], off offset:272
	global_load_dwordx4 v[56:59], v[174:175], off offset:256
	v_pk_mul_f32 v[48:49], v[26:27], v[48:49] op_sel_hi:[0,1]
	v_pk_mul_f32 v[44:45], v[26:27], v[44:45] op_sel_hi:[0,1]
	v_pk_mul_f32 v[50:51], v[26:27], v[50:51] op_sel_hi:[0,1]
	v_pk_mul_f32 v[46:47], v[26:27], v[46:47] op_sel_hi:[0,1]
	s_waitcnt vmcnt(0)
	v_mov_b32_e32 v61, v58
	v_mov_b32_e32 v58, v57
	v_mov_b32_e32 v57, v54
	v_mov_b32_e32 v54, v53
	v_mov_b32_e32 v60, v56
	v_pk_mul_f32 v[48:49], v[58:59], v[48:49]
	v_mov_b32_e32 v56, v52
	v_pk_mul_f32 v[44:45], v[54:55], v[44:45]
	v_pk_mul_f32 v[50:51], v[60:61], v[50:51]
	v_pk_mul_f32 v[46:47], v[56:57], v[46:47]
	v_bfe_u32 v17, v45, 16, 1
	v_bfe_u32 v19, v44, 16, 1
	v_bfe_u32 v52, v49, 16, 1
	v_bfe_u32 v53, v48, 16, 1
	v_add3_u32 v48, v48, v53, s64
	v_add3_u32 v49, v49, v52, s64
	v_add3_u32 v19, v44, v19, s64
	v_add3_u32 v17, v45, v17, s64
	v_bfe_u32 v44, v50, 16, 1
	v_bfe_u32 v45, v51, 16, 1
	v_bfe_u32 v52, v46, 16, 1
	v_bfe_u32 v53, v47, 16, 1
	v_add3_u32 v47, v47, v53, s64
	v_add3_u32 v46, v46, v52, s64
	v_add3_u32 v45, v51, v45, s64
	v_add3_u32 v44, v50, v44, s64
	v_lshrrev_b32_e32 v44, 16, v44
	v_lshrrev_b32_e32 v45, 16, v45
	v_lshrrev_b32_e32 v46, 16, v46
	v_lshrrev_b32_e32 v47, 16, v47
	v_and_or_b32 v117, v17, s3, v47
	v_and_or_b32 v116, v19, s3, v46
	v_and_or_b32 v115, v49, s3, v45
	v_and_or_b32 v114, v48, s3, v44
	global_load_dwordx4 v[44:47], v[174:175], off offset:336
	global_load_dwordx4 v[48:51], v[174:175], off offset:320
	v_pk_mul_f32 v[40:41], v[26:27], v[40:41] op_sel_hi:[0,1]
	v_pk_mul_f32 v[36:37], v[26:27], v[36:37] op_sel_hi:[0,1]
	v_pk_mul_f32 v[42:43], v[26:27], v[42:43] op_sel_hi:[0,1]
	v_pk_mul_f32 v[38:39], v[26:27], v[38:39] op_sel_hi:[0,1]
	s_waitcnt vmcnt(0)
	v_mov_b32_e32 v53, v50
	v_mov_b32_e32 v50, v49
	v_mov_b32_e32 v49, v46
	v_mov_b32_e32 v46, v45
	v_mov_b32_e32 v52, v48
	v_pk_mul_f32 v[40:41], v[50:51], v[40:41]
	v_mov_b32_e32 v48, v44
	v_pk_mul_f32 v[36:37], v[46:47], v[36:37]
	v_pk_mul_f32 v[42:43], v[52:53], v[42:43]
	v_pk_mul_f32 v[38:39], v[48:49], v[38:39]
	v_bfe_u32 v17, v37, 16, 1
	v_bfe_u32 v19, v36, 16, 1
	v_bfe_u32 v44, v41, 16, 1
	v_bfe_u32 v45, v40, 16, 1
	v_add3_u32 v40, v40, v45, s64
	v_add3_u32 v41, v41, v44, s64
	v_add3_u32 v19, v36, v19, s64
	v_add3_u32 v17, v37, v17, s64
	v_bfe_u32 v36, v42, 16, 1
	v_bfe_u32 v37, v43, 16, 1
	v_bfe_u32 v44, v38, 16, 1
	v_bfe_u32 v45, v39, 16, 1
	v_add3_u32 v39, v39, v45, s64
	v_add3_u32 v38, v38, v44, s64
	v_add3_u32 v37, v43, v37, s64
	v_add3_u32 v36, v42, v36, s64
	v_lshrrev_b32_e32 v36, 16, v36
	v_lshrrev_b32_e32 v37, 16, v37
	v_lshrrev_b32_e32 v38, 16, v38
	v_lshrrev_b32_e32 v39, 16, v39
	v_and_or_b32 v121, v17, s3, v39
	v_and_or_b32 v120, v19, s3, v38
	v_and_or_b32 v119, v41, s3, v37
	v_and_or_b32 v118, v40, s3, v36
	global_load_dwordx4 v[36:39], v[174:175], off offset:400
	global_load_dwordx4 v[40:43], v[174:175], off offset:384
	v_pk_mul_f32 v[32:33], v[26:27], v[32:33] op_sel_hi:[0,1]
	v_pk_mul_f32 v[28:29], v[26:27], v[28:29] op_sel_hi:[0,1]
	v_pk_mul_f32 v[34:35], v[26:27], v[34:35] op_sel_hi:[0,1]
	v_pk_mul_f32 v[30:31], v[26:27], v[30:31] op_sel_hi:[0,1]
	s_waitcnt vmcnt(0)
	v_mov_b32_e32 v45, v42
	v_mov_b32_e32 v42, v41
	v_mov_b32_e32 v41, v38
	v_mov_b32_e32 v38, v37
	v_mov_b32_e32 v44, v40
	v_pk_mul_f32 v[32:33], v[42:43], v[32:33]
	v_mov_b32_e32 v40, v36
	v_pk_mul_f32 v[28:29], v[38:39], v[28:29]
	v_pk_mul_f32 v[34:35], v[44:45], v[34:35]
	v_pk_mul_f32 v[30:31], v[40:41], v[30:31]
	v_bfe_u32 v17, v29, 16, 1
	v_bfe_u32 v19, v28, 16, 1
	v_bfe_u32 v36, v33, 16, 1
	v_bfe_u32 v37, v32, 16, 1
	v_add3_u32 v32, v32, v37, s64
	v_add3_u32 v33, v33, v36, s64
	v_add3_u32 v19, v28, v19, s64
	v_add3_u32 v17, v29, v17, s64
	v_bfe_u32 v28, v34, 16, 1
	v_bfe_u32 v29, v35, 16, 1
	v_bfe_u32 v36, v30, 16, 1
	v_bfe_u32 v37, v31, 16, 1
	v_add3_u32 v31, v31, v37, s64
	v_add3_u32 v30, v30, v36, s64
	v_add3_u32 v29, v35, v29, s64
	v_add3_u32 v28, v34, v28, s64
	v_lshrrev_b32_e32 v28, 16, v28
	v_lshrrev_b32_e32 v29, 16, v29
	v_lshrrev_b32_e32 v30, 16, v30
	v_lshrrev_b32_e32 v31, 16, v31
	v_and_or_b32 v125, v17, s3, v31
	v_and_or_b32 v124, v19, s3, v30
	v_and_or_b32 v123, v33, s3, v29
	v_and_or_b32 v122, v32, s3, v28
	global_load_dwordx4 v[28:31], v[174:175], off offset:448
	global_load_dwordx4 v[32:35], v[174:175], off offset:464
	v_mov_b32_e32 v17, v20
	v_pk_mul_f32 v[24:25], v[26:27], v[24:25] op_sel_hi:[0,1]
	v_mov_b32_e32 v19, v21
	v_pk_mul_f32 v[16:17], v[26:27], v[16:17] op_sel_hi:[0,1]
	v_pk_mul_f32 v[22:23], v[26:27], v[22:23] op_sel_hi:[0,1]
	v_pk_mul_f32 v[18:19], v[26:27], v[18:19] op_sel_hi:[0,1]
	s_waitcnt vmcnt(1)
	v_mov_b32_e32 v20, v28
	v_mov_b32_e32 v21, v30
	v_mov_b32_e32 v30, v29
	s_waitcnt vmcnt(0)
	v_mov_b32_e32 v28, v32
	v_mov_b32_e32 v29, v34
	v_mov_b32_e32 v34, v33
	v_pk_mul_f32 v[20:21], v[20:21], v[24:25]
	v_pk_mul_f32 v[16:17], v[28:29], v[16:17]
	v_pk_mul_f32 v[22:23], v[30:31], v[22:23]
	v_pk_mul_f32 v[18:19], v[34:35], v[18:19]
	v_bfe_u32 v29, v20, 16, 1
	v_bfe_u32 v30, v21, 16, 1
	v_bfe_u32 v31, v16, 16, 1
	v_bfe_u32 v32, v17, 16, 1
	v_bfe_u32 v24, v19, 16, 1
	v_bfe_u32 v25, v18, 16, 1
	v_bfe_u32 v26, v23, 16, 1
	v_bfe_u32 v28, v22, 16, 1
	v_add3_u32 v17, v17, v32, s64
	v_add3_u32 v16, v16, v31, s64
	v_add3_u32 v21, v21, v30, s64
	v_add3_u32 v20, v20, v29, s64
	v_add3_u32 v22, v22, v28, s64
	v_add3_u32 v23, v23, v26, s64
	v_add3_u32 v18, v18, v25, s64
	v_add3_u32 v19, v19, v24, s64
	v_lshrrev_b32_e32 v20, 16, v20
	v_lshrrev_b32_e32 v21, 16, v21
	v_lshrrev_b32_e32 v16, 16, v16
	v_lshrrev_b32_e32 v17, 16, v17
	v_and_or_b32 v129, v19, s3, v17
	v_and_or_b32 v128, v18, s3, v16
	v_and_or_b32 v127, v23, s3, v21
	v_and_or_b32 v126, v22, s3, v20
	global_load_dwordx4 v[30:33], v[192:193], off
	global_load_dwordx3 v[16:18], v[192:193], off offset:16
	global_load_dword v42, v[190:191], off
	global_load_dword v40, v[190:191], off offset:128
	v_cvt_f32_i32_e32 v146, v27
	v_lshlrev_b32_e32 v24, 16, v6
	v_and_b32_e32 v20, 0xffff0000, v6
	v_and_b32_e32 v23, 0xffff0000, v7
	v_lshlrev_b32_e32 v22, 16, v7
	v_lshlrev_b32_e32 v47, 16, v13
	v_lshlrev_b32_e32 v46, 16, v12
	v_and_b32_e32 v45, 0xffff0000, v13
	v_and_b32_e32 v44, 0xffff0000, v12
	v_lshlrev_b32_e32 v49, 16, v9
	v_lshlrev_b32_e32 v48, 16, v8
	v_and_b32_e32 v51, 0xffff0000, v9
	v_and_b32_e32 v50, 0xffff0000, v8
	v_pk_mul_f32 v[56:57], v[22:23], v[22:23]
	v_pk_mul_f32 v[62:63], v[46:47], v[46:47]
	v_pk_mul_f32 v[64:65], v[44:45], v[44:45]
	v_pk_mul_f32 v[58:59], v[48:49], v[48:49]
	v_pk_mul_f32 v[60:61], v[50:51], v[50:51]
	s_waitcnt vmcnt(3)
	v_mul_f32_e32 v6, v30, v146
	v_cvt_f64_f32_e32 v[6:7], v6
	v_mul_f64 v[12:13], v[6:7], s[82:83]
	v_rndne_f64_e32 v[12:13], v[12:13]
	v_fma_f64 v[6:7], v[6:7], s[82:83], -v[12:13]
	v_cvt_f32_f64_e32 v6, v[6:7]
	v_cos_f32_e32 v12, v6
	v_sin_f32_e32 v26, v6
	global_load_dword v54, v[190:191], off offset:4
	global_load_dword v52, v[190:191], off offset:132
	global_load_dword v43, v[190:191], off offset:8
	global_load_dword v41, v[190:191], off offset:136
	v_mul_f32_e32 v6, v31, v146
	v_cvt_f64_f32_e32 v[6:7], v6
	v_mul_f64 v[8:9], v[6:7], s[82:83]
	v_rndne_f64_e32 v[8:9], v[8:9]
	v_fma_f64 v[6:7], v[6:7], s[82:83], -v[8:9]
	v_cvt_f32_f64_e32 v6, v[6:7]
	v_cos_f32_e32 v28, v6
	v_sin_f32_e32 v30, v6
	global_load_dword v55, v[190:191], off offset:12
	global_load_dword v53, v[190:191], off offset:140
	v_mul_f32_e32 v6, v32, v146
	v_cvt_f64_f32_e32 v[6:7], v6
	v_mul_f64 v[8:9], v[6:7], s[82:83]
	v_rndne_f64_e32 v[8:9], v[8:9]
	v_fma_f64 v[6:7], v[6:7], s[82:83], -v[8:9]
	v_cvt_f32_f64_e32 v6, v[6:7]
	v_cos_f32_e32 v13, v6
	v_sin_f32_e32 v27, v6
	v_mul_f32_e32 v6, v33, v146
	v_cvt_f64_f32_e32 v[6:7], v6
	v_mul_f64 v[8:9], v[6:7], s[82:83]
	v_rndne_f64_e32 v[8:9], v[8:9]
	v_fma_f64 v[6:7], v[6:7], s[82:83], -v[8:9]
	v_cvt_f32_f64_e32 v6, v[6:7]
	v_cos_f32_e32 v29, v6
	v_sin_f32_e32 v31, v6
	global_load_dword v70, v[190:191], off offset:16
	global_load_dword v68, v[190:191], off offset:144
	s_waitcnt vmcnt(10)
	v_mul_f32_e32 v6, v16, v146
	v_cvt_f64_f32_e32 v[6:7], v6
	v_mul_f64 v[8:9], v[6:7], s[82:83]
	v_rndne_f64_e32 v[8:9], v[8:9]
	v_fma_f64 v[6:7], v[6:7], s[82:83], -v[8:9]
	v_cvt_f32_f64_e32 v6, v[6:7]
	v_cos_f32_e32 v16, v6
	v_sin_f32_e32 v32, v6
	v_lshlrev_b32_e32 v67, 16, v15
	v_lshlrev_b32_e32 v66, 16, v14
	v_and_b32_e32 v35, 0xffff0000, v15
	v_and_b32_e32 v34, 0xffff0000, v14
	v_lshlrev_b32_e32 v39, 16, v11
	v_lshlrev_b32_e32 v38, 16, v10
	v_and_b32_e32 v37, 0xffff0000, v11
	v_and_b32_e32 v36, 0xffff0000, v10
	v_pk_mul_f32 v[76:77], v[66:67], v[66:67]
	v_pk_mul_f32 v[78:79], v[34:35], v[34:35]
	v_pk_mul_f32 v[72:73], v[38:39], v[38:39]
	v_pk_mul_f32 v[74:75], v[36:37], v[36:37]
	global_load_dword v82, v[190:191], off offset:20
	global_load_dword v80, v[190:191], off offset:148
	global_load_dword v71, v[190:191], off offset:24
	global_load_dword v69, v[190:191], off offset:152
	v_mul_f32_e32 v6, v17, v146
	v_cvt_f64_f32_e32 v[6:7], v6
	v_mul_f64 v[8:9], v[6:7], s[82:83]
	v_rndne_f64_e32 v[8:9], v[8:9]
	v_fma_f64 v[6:7], v[6:7], s[82:83], -v[8:9]
	v_cvt_f32_f64_e32 v6, v[6:7]
	v_cos_f32_e32 v84, v6
	v_sin_f32_e32 v86, v6
	global_load_dword v10, v[196:197], off
	global_load_dword v83, v[194:195], off
	global_load_dword v81, v[194:195], off offset:128
	v_mul_f32_e32 v6, v18, v146
	v_cvt_f64_f32_e32 v[6:7], v6
	v_mul_f64 v[8:9], v[6:7], s[82:83]
	v_rndne_f64_e32 v[8:9], v[8:9]
	v_fma_f64 v[6:7], v[6:7], s[82:83], -v[8:9]
	v_cvt_f32_f64_e32 v6, v[6:7]
	v_cos_f32_e32 v17, v6
	v_sin_f32_e32 v33, v6
	s_waitcnt vmcnt(2)
	v_mul_f32_e32 v6, v10, v146
	v_cvt_f64_f32_e32 v[6:7], v6
	v_mul_f64 v[8:9], v[6:7], s[82:83]
	v_rndne_f64_e32 v[8:9], v[8:9]
	v_fma_f64 v[6:7], v[6:7], s[82:83], -v[8:9]
	v_cvt_f32_f64_e32 v6, v[6:7]
	v_cos_f32_e32 v85, v6
	v_sin_f32_e32 v87, v6
	global_load_dwordx4 v[6:9], v[192:193], off offset:80
	global_load_dwordx4 v[148:151], v[192:193], off offset:64
	global_load_dword v138, v[190:191], off offset:64
	global_load_dword v94, v[190:191], off offset:192
	v_lshlrev_b32_e32 v89, 16, v1
	v_lshlrev_b32_e32 v88, 16, v0
	v_and_b32_e32 v19, 0xffff0000, v1
	v_and_b32_e32 v18, 0xffff0000, v0
	v_lshlrev_b32_e32 v93, 16, v5
	v_lshlrev_b32_e32 v92, 16, v4
	v_and_b32_e32 v91, 0xffff0000, v5
	v_and_b32_e32 v90, 0xffff0000, v4
	v_pk_mul_f32 v[134:135], v[88:89], v[88:89]
	v_pk_mul_f32 v[136:137], v[18:19], v[18:19]
	v_pk_mul_f32 v[130:131], v[92:93], v[92:93]
	v_pk_mul_f32 v[132:133], v[90:91], v[90:91]
	s_waitcnt vmcnt(2)
	v_mul_f32_e32 v10, v148, v146
	v_cvt_f64_f32_e32 v[10:11], v10
	v_mul_f64 v[14:15], v[10:11], s[82:83]
	v_rndne_f64_e32 v[14:15], v[14:15]
	v_fma_f64 v[10:11], v[10:11], s[82:83], -v[14:15]
	v_cvt_f32_f64_e32 v11, v[10:11]
	v_cos_f32_e32 v10, v11
	v_sin_f32_e32 v14, v11
	global_load_dword v144, v[190:191], off offset:68
	global_load_dword v142, v[190:191], off offset:196
	global_load_dword v139, v[190:191], off offset:72
	global_load_dword v95, v[190:191], off offset:200
	v_mul_f32_e32 v0, v149, v146
	v_cvt_f64_f32_e32 v[0:1], v0
	v_mul_f64 v[4:5], v[0:1], s[82:83]
	v_rndne_f64_e32 v[4:5], v[4:5]
	v_fma_f64 v[0:1], v[0:1], s[82:83], -v[4:5]
	v_cvt_f32_f64_e32 v1, v[0:1]
	v_cos_f32_e32 v0, v1
	v_sin_f32_e32 v4, v1
	global_load_dword v145, v[190:191], off offset:76
	global_load_dword v143, v[190:191], off offset:204
	v_mul_f32_e32 v1, v150, v146
	v_cvt_f64_f32_e32 v[140:141], v1
	v_mul_f64 v[148:149], v[140:141], s[82:83]
	v_rndne_f64_e32 v[148:149], v[148:149]
	v_fma_f64 v[140:141], v[140:141], s[82:83], -v[148:149]
	v_cvt_f32_f64_e32 v1, v[140:141]
	v_cos_f32_e32 v11, v1
	v_sin_f32_e32 v15, v1
	v_mul_f32_e32 v1, v151, v146
	v_cvt_f64_f32_e32 v[140:141], v1
	v_mul_f64 v[148:149], v[140:141], s[82:83]
	v_rndne_f64_e32 v[148:149], v[148:149]
	v_fma_f64 v[140:141], v[140:141], s[82:83], -v[148:149]
	v_cvt_f32_f64_e32 v5, v[140:141]
	v_cos_f32_e32 v1, v5
	v_sin_f32_e32 v5, v5
	v_mul_f32_e32 v6, v6, v146
	v_cvt_f64_f32_e32 v[140:141], v6
	v_add_f32_e32 v6, v62, v64
	v_add_f32_e32 v6, v6, v63
	v_add_f32_e32 v6, v6, v65
	v_add_f32_e32 v6, v6, v76
	v_add_f32_e32 v6, v6, v78
	v_add_f32_e32 v6, v6, v77
	v_add_f32_e32 v6, v6, v79
	v_add_f32_e32 v6, v6, v134
	v_mul_f64 v[148:149], v[140:141], s[82:83]
	v_add_f32_e32 v6, v6, v136
	v_rndne_f64_e32 v[148:149], v[148:149]
	v_lshlrev_b32_e32 v151, 16, v3
	v_lshlrev_b32_e32 v150, 16, v2
	v_add_f32_e32 v6, v6, v135
	v_fma_f64 v[148:149], v[140:141], s[82:83], -v[148:149]
	v_pk_mul_f32 v[152:153], v[150:151], v[150:151]
	v_and_b32_e32 v141, 0xffff0000, v3
	v_and_b32_e32 v140, 0xffff0000, v2
	v_add_f32_e32 v6, v6, v137
	v_pk_mul_f32 v[2:3], v[140:141], v[140:141]
	v_add_f32_e32 v6, v6, v152
	v_add_f32_e32 v2, v6, v2
	v_add_f32_e32 v2, v2, v153
	v_add_f32_e32 v2, v2, v3
	v_add_f32_e32 v2, v2, v58
	v_add_f32_e32 v2, v2, v60
	v_add_f32_e32 v2, v2, v59
	v_add_f32_e32 v2, v2, v61
	v_add_f32_e32 v2, v2, v72
	v_add_f32_e32 v2, v2, v74
	v_add_f32_e32 v2, v2, v73
	v_add_f32_e32 v2, v2, v75
	v_add_f32_e32 v2, v2, v130
	v_add_f32_e32 v2, v2, v132
	v_add_f32_e32 v2, v2, v131
	v_add_f32_e32 v2, v2, v133
	v_fmac_f32_e32 v2, v24, v24
	v_fmac_f32_e32 v2, v20, v20
	v_add_f32_e32 v2, v2, v56
	v_add_f32_e32 v2, v2, v57
	v_mov_b32_e32 v3, v2
	s_nop 1
	v_permlane32_swap_b32_e32 v2, v3
	v_add_f32_e32 v2, v2, v3
	v_fmamk_f32 v2, v2, 0x3c800000, v253
	v_rsq_f32_e32 v3, v2
	v_cvt_f32_f64_e32 v6, v[148:149]
	v_cos_f32_e32 v2, v6
	v_sin_f32_e32 v6, v6
	v_mul_f32_e32 v56, 0x3d93cd3a, v3
	v_pk_mul_f32 v[44:45], v[56:57], v[44:45] op_sel_hi:[0,1]
	v_pk_mul_f32 v[44:45], v[54:55], v[44:45]
	global_load_dword v54, v[190:191], off offset:80
	global_load_dword v58, v[190:191], off offset:208
	v_pk_mul_f32 v[46:47], v[56:57], v[46:47] op_sel_hi:[0,1]
	v_pk_mul_f32 v[42:43], v[42:43], v[46:47]
	v_pk_mul_f32 v[46:47], v[56:57], v[48:49] op_sel_hi:[0,1]
	v_pk_mul_f32 v[40:41], v[40:41], v[46:47]
	v_pk_mul_f32 v[46:47], v[56:57], v[50:51] op_sel_hi:[0,1]
	v_pk_mul_f32 v[46:47], v[52:53], v[46:47]
	v_pk_mul_f32 v[48:49], v[42:43], v[26:27]
	v_pk_mul_f32 v[52:53], v[56:57], v[66:67] op_sel_hi:[0,1]
	v_pk_mul_f32 v[38:39], v[56:57], v[38:39] op_sel_hi:[0,1]
	v_pk_mul_f32 v[26:27], v[40:41], v[26:27]
	v_pk_fma_f32 v[48:49], v[40:41], v[12:13], v[48:49]
	v_pk_mul_f32 v[50:51], v[44:45], v[30:31]
	v_pk_mul_f32 v[52:53], v[70:71], v[52:53]
	v_pk_mul_f32 v[38:39], v[68:69], v[38:39]
	v_pk_mul_f32 v[36:37], v[56:57], v[36:37] op_sel_hi:[0,1]
	v_pk_fma_f32 v[12:13], v[42:43], v[12:13], v[26:27] neg_lo:[0,0,1] neg_hi:[0,0,1]
	v_pk_mul_f32 v[26:27], v[46:47], v[30:31]
	v_pk_fma_f32 v[50:51], v[46:47], v[28:29], v[50:51]
	v_pk_mul_f32 v[34:35], v[56:57], v[34:35] op_sel_hi:[0,1]
	v_pk_mul_f32 v[36:37], v[80:81], v[36:37]
	v_pk_mul_f32 v[60:61], v[52:53], v[32:33]
	v_pk_fma_f32 v[26:27], v[44:45], v[28:29], v[26:27] neg_lo:[0,0,1] neg_hi:[0,0,1]
	v_pk_mul_f32 v[28:29], v[38:39], v[32:33]
	v_pk_mul_f32 v[34:35], v[82:83], v[34:35]
	v_pk_fma_f32 v[60:61], v[38:39], v[16:17], v[60:61]
	v_pk_fma_f32 v[16:17], v[52:53], v[16:17], v[28:29] neg_lo:[0,0,1] neg_hi:[0,0,1]
	v_pk_mul_f32 v[28:29], v[36:37], v[86:87]
	v_bfe_u32 v25, v27, 16, 1
	v_pk_fma_f32 v[28:29], v[34:35], v[84:85], v[28:29] neg_lo:[0,0,1] neg_hi:[0,0,1]
	v_bfe_u32 v30, v26, 16, 1
	v_bfe_u32 v3, v29, 16, 1
	v_bfe_u32 v21, v28, 16, 1
	v_add3_u32 v21, v28, v21, s64
	v_add3_u32 v3, v29, v3, s64
	v_bfe_u32 v28, v13, 16, 1
	v_bfe_u32 v29, v16, 16, 1
	v_add3_u32 v25, v27, v25, s64
	v_bfe_u32 v27, v12, 16, 1
	v_add3_u32 v16, v16, v29, s64
	v_add3_u32 v13, v13, v28, s64
	v_pk_mul_f32 v[62:63], v[34:35], v[86:87]
	v_add3_u32 v26, v26, v30, s64
	v_bfe_u32 v30, v17, 16, 1
	v_add3_u32 v12, v12, v27, s64
	v_lshrrev_b32_e32 v13, 16, v13
	v_lshrrev_b32_e32 v16, 16, v16
	v_pk_fma_f32 v[62:63], v[36:37], v[84:85], v[62:63]
	v_add3_u32 v17, v17, v30, s64
	v_lshrrev_b32_e32 v12, 16, v12
	v_and_or_b32 v132, v21, s3, v16
	v_and_or_b32 v131, v25, s3, v13
	v_bfe_u32 v21, v49, 16, 1
	v_bfe_u32 v25, v60, 16, 1
	v_lshrrev_b32_e32 v17, 16, v17
	v_and_or_b32 v130, v26, s3, v12
	v_bfe_u32 v12, v62, 16, 1
	v_bfe_u32 v13, v51, 16, 1
	v_bfe_u32 v26, v61, 16, 1
	v_add3_u32 v25, v60, v25, s64
	v_add3_u32 v21, v49, v21, s64
	v_and_or_b32 v133, v3, s3, v17
	v_bfe_u32 v3, v63, 16, 1
	v_add3_u32 v13, v51, v13, s64
	v_add3_u32 v12, v62, v12, s64
	v_add3_u32 v26, v61, v26, s64
	v_lshrrev_b32_e32 v21, 16, v21
	v_lshrrev_b32_e32 v25, 16, v25
	v_add3_u32 v3, v63, v3, s64
	v_lshrrev_b32_e32 v26, 16, v26
	v_and_or_b32 v136, v12, s3, v25
	v_and_or_b32 v135, v13, s3, v21
	v_pk_mul_f32 v[12:13], v[56:57], v[88:89] op_sel_hi:[0,1]
	v_bfe_u32 v17, v48, 16, 1
	v_and_or_b32 v137, v3, s3, v26
	s_waitcnt vmcnt(5)
	v_pk_mul_f32 v[26:27], v[138:139], v[12:13]
	v_pk_mul_f32 v[12:13], v[56:57], v[92:93] op_sel_hi:[0,1]
	v_bfe_u32 v16, v50, 16, 1
	v_add3_u32 v17, v48, v17, s64
	s_waitcnt vmcnt(4)
	v_pk_mul_f32 v[28:29], v[94:95], v[12:13]
	v_pk_mul_f32 v[12:13], v[56:57], v[18:19] op_sel_hi:[0,1]
	v_add3_u32 v16, v50, v16, s64
	v_lshrrev_b32_e32 v17, 16, v17
	s_waitcnt vmcnt(3)
	v_pk_mul_f32 v[18:19], v[144:145], v[12:13]
	v_pk_mul_f32 v[12:13], v[56:57], v[90:91] op_sel_hi:[0,1]
	v_and_or_b32 v134, v16, s3, v17
	s_waitcnt vmcnt(2)
	v_pk_mul_f32 v[30:31], v[142:143], v[12:13]
	v_pk_mul_f32 v[12:13], v[26:27], v[14:15]
	v_pk_mul_f32 v[16:17], v[18:19], v[4:5]
	v_pk_fma_f32 v[12:13], v[28:29], v[10:11], v[12:13]
	v_pk_fma_f32 v[16:17], v[30:31], v[0:1], v[16:17]
	global_load_dword v32, v[190:191], off offset:84
	global_load_dword v34, v[190:191], off offset:212
	global_load_dword v55, v[190:191], off offset:88
	global_load_dword v59, v[190:191], off offset:216
	v_mul_f32_e32 v3, v7, v146
	v_cvt_f64_f32_e32 v[38:39], v3
	v_mul_f64 v[40:41], v[38:39], s[82:83]
	v_rndne_f64_e32 v[40:41], v[40:41]
	v_fma_f64 v[38:39], v[38:39], s[82:83], -v[40:41]
	v_cvt_f32_f64_e32 v3, v[38:39]
	v_mov_b32_e32 v25, v22
	v_cos_f32_e32 v22, v3
	v_sin_f32_e32 v38, v3
	v_pk_mul_f32 v[36:37], v[56:57], v[150:151] op_sel_hi:[0,1]
	v_pk_mul_f32 v[24:25], v[56:57], v[24:25] op_sel_hi:[0,1]
	s_waitcnt vmcnt(1)
	v_pk_mul_f32 v[36:37], v[54:55], v[36:37]
	s_waitcnt vmcnt(0)
	v_pk_mul_f32 v[24:25], v[58:59], v[24:25]
	global_load_dword v33, v[190:191], off offset:92
	global_load_dword v35, v[190:191], off offset:220
	v_mov_b32_e32 v21, v23
	v_pk_mul_f32 v[20:21], v[56:57], v[20:21] op_sel_hi:[0,1]
	v_mul_f32_e32 v3, v8, v146
	v_pk_mul_f32 v[40:41], v[56:57], v[140:141] op_sel_hi:[0,1]
	v_mul_f32_e32 v8, v9, v146
	v_cvt_f64_f32_e32 v[8:9], v8
	s_waitcnt vmcnt(1)
	v_pk_mul_f32 v[32:33], v[32:33], v[40:41]
	s_waitcnt vmcnt(0)
	v_pk_mul_f32 v[20:21], v[34:35], v[20:21]
	v_cvt_f64_f32_e32 v[34:35], v3
	v_mul_f64 v[40:41], v[34:35], s[82:83]
	v_rndne_f64_e32 v[40:41], v[40:41]
	v_fma_f64 v[34:35], v[34:35], s[82:83], -v[40:41]
	v_mul_f64 v[40:41], v[8:9], s[82:83]
	v_rndne_f64_e32 v[40:41], v[40:41]
	v_fma_f64 v[8:9], v[8:9], s[82:83], -v[40:41]
	v_cvt_f32_f64_e32 v7, v[34:35]
	v_cvt_f32_f64_e32 v8, v[8:9]
	v_cos_f32_e32 v3, v7
	v_sin_f32_e32 v7, v7
	v_sin_f32_e32 v39, v8
	v_cos_f32_e32 v23, v8
	v_pk_mul_f32 v[34:35], v[36:37], v[6:7]
	v_pk_mul_f32 v[8:9], v[32:33], v[38:39]
	v_pk_fma_f32 v[34:35], v[24:25], v[2:3], v[34:35]
	v_pk_fma_f32 v[8:9], v[20:21], v[22:23], v[8:9]
	v_pk_mul_f32 v[4:5], v[30:31], v[4:5]
	v_pk_mul_f32 v[14:15], v[28:29], v[14:15]
	v_pk_fma_f32 v[0:1], v[18:19], v[0:1], v[4:5] neg_lo:[0,0,1] neg_hi:[0,0,1]
	v_pk_mul_f32 v[4:5], v[24:25], v[6:7]
	v_pk_fma_f32 v[10:11], v[26:27], v[10:11], v[14:15] neg_lo:[0,0,1] neg_hi:[0,0,1]
	v_pk_fma_f32 v[2:3], v[36:37], v[2:3], v[4:5] neg_lo:[0,0,1] neg_hi:[0,0,1]
	v_pk_mul_f32 v[4:5], v[20:21], v[38:39]
	v_bfe_u32 v6, v1, 16, 1
	v_pk_fma_f32 v[4:5], v[32:33], v[22:23], v[4:5] neg_lo:[0,0,1] neg_hi:[0,0,1]
	v_bfe_u32 v7, v0, 16, 1
	v_bfe_u32 v14, v5, 16, 1
	v_bfe_u32 v15, v4, 16, 1
	v_add3_u32 v4, v4, v15, s64
	v_add3_u32 v5, v5, v14, s64
	v_bfe_u32 v14, v10, 16, 1
	v_bfe_u32 v15, v11, 16, 1
	v_add3_u32 v0, v0, v7, s64
	v_add3_u32 v1, v1, v6, s64
	v_bfe_u32 v6, v2, 16, 1
	v_bfe_u32 v7, v3, 16, 1
	v_add3_u32 v11, v11, v15, s64
	v_add3_u32 v10, v10, v14, s64
	v_add3_u32 v3, v3, v7, s64
	v_add3_u32 v2, v2, v6, s64
	v_lshrrev_b32_e32 v6, 16, v10
	v_lshrrev_b32_e32 v7, 16, v11
	v_lshrrev_b32_e32 v2, 16, v2
	v_lshrrev_b32_e32 v3, 16, v3
	v_and_or_b32 v139, v1, s3, v7
	v_and_or_b32 v138, v0, s3, v6
	v_bfe_u32 v6, v12, 16, 1
	v_bfe_u32 v7, v13, 16, 1
	v_and_or_b32 v141, v5, s3, v3
	v_and_or_b32 v140, v4, s3, v2
	v_bfe_u32 v0, v17, 16, 1
	v_bfe_u32 v1, v16, 16, 1
	v_bfe_u32 v4, v34, 16, 1
	v_bfe_u32 v5, v35, 16, 1
	v_add3_u32 v7, v13, v7, s64
	v_add3_u32 v6, v12, v6, s64
	v_bfe_u32 v2, v9, 16, 1
	v_bfe_u32 v3, v8, 16, 1
	v_add3_u32 v1, v16, v1, s64
	v_add3_u32 v0, v17, v0, s64
	v_add3_u32 v5, v35, v5, s64
	v_add3_u32 v4, v34, v4, s64
	v_lshrrev_b32_e32 v6, 16, v6
	v_lshrrev_b32_e32 v7, 16, v7
	v_add3_u32 v3, v8, v3, s64
	v_add3_u32 v2, v9, v2, s64
	v_lshrrev_b32_e32 v4, 16, v4
	v_lshrrev_b32_e32 v5, 16, v5
	v_and_or_b32 v143, v0, s3, v7
	v_and_or_b32 v142, v1, s3, v6
	s_lshr_b32 s55, s2, 6
	s_add_i32 s55, s55, 3
	s_cmp_lg_u64 s[30:31], 0
	s_cselect_b32 s55, s55, 0
	s_mul_i32 s56, s55, 0x30000
	s_add_u32 s36, s36, s56
	s_addc_u32 s37, s37, 0
	s_lshl_b32 s56, s55, 13
	s_add_u32 vcc_lo, vcc_lo, s56
	s_addc_u32 vcc_hi, vcc_hi, 0
	v_lshl_add_u64 v[0:1], v[176:177], 1, s[36:37]
	v_mov_b32_e32 v203, v97
	v_and_or_b32 v145, v2, s3, v5
	v_and_or_b32 v144, v3, s3, v4
	v_lshl_add_u64 v[8:9], v[0:1], 0, v[202:203]
	v_lshl_add_u64 v[4:5], v[178:179], 1, s[36:37]
	v_lshl_add_u64 v[16:17], vcc, 0, v[180:181]
	v_mov_b32_e32 v205, v97
	global_load_dwordx4 v[0:3], v[8:9], off offset:256
	v_lshl_add_u64 v[12:13], v[4:5], 0, v[202:203]
	v_lshl_add_u64 v[16:17], v[16:17], 0, v[204:205]
	global_load_dwordx4 v[4:7], v[12:13], off offset:256
	s_nop 0
	global_load_dwordx4 v[8:11], v[8:9], off
	s_nop 0
	global_load_dwordx4 v[12:15], v[12:13], off
	v_readfirstlane_b32 s55, v215
	global_load_dwordx4 v[16:19], v[16:17], off
	s_ashr_i32 s56, s55, 6
	s_cmp_gt_i32 s56, 3
	s_cselect_b64 s[80:81], -1, 0
	s_cmp_lt_i32 s56, 4
	s_cselect_b64 s[76:77], -1, 0
	s_and_b32 s55, s55, 0x3fffffc0
	s_lshl_b32 s55, s55, 2
	s_waitcnt vmcnt(0)
	s_lshr_b32 s63, s2, 6
	s_lshl_b32 s56, s56, 5
	s_add_i32 s69, s55, 0
	v_add_u32_e32 v20, 0, v216
	s_add_i32 s33, s63, 4
	s_add_i32 s2, s56, s2
	s_add_i32 s69, s69, 0x18000
	s_waitcnt vmcnt(4)
	ds_write_b128 v20, v[0:3]
	v_add_u32_e32 v0, 0, v217
	s_waitcnt vmcnt(3)
	ds_write_b128 v0, v[4:7]
	s_waitcnt vmcnt(2)
	ds_write_b128 v219, v[8:11] offset:49152
	s_waitcnt vmcnt(1)
	ds_write_b128 v219, v[12:15] offset:57344
	s_waitcnt vmcnt(0)
	ds_write_b128 v220, v[16:19]
	s_sub_u32 m0, s100, 0x2000
	s_add_u32 vcc_lo, vcc_lo, m0
	s_addc_u32 vcc_hi, vcc_hi, s101
	s_mul_i32 m0, m0, 24
	s_add_u32 s36, s36, m0
	s_addc_u32 s37, s37, s101
	v_lshl_add_u64 v[0:1], v[182:183], 1, s[36:37]
	v_lshl_add_u64 v[0:1], v[0:1], 0, v[202:203]
	v_lshl_add_u64 v[2:3], v[184:185], 1, s[36:37]
	v_lshl_add_u64 v[2:3], v[2:3], 0, v[202:203]
	global_load_dwordx4 v[146:149], v[0:1], off offset:256
	global_load_dwordx4 v[150:153], v[0:1], off
	global_load_dwordx4 v[154:157], v[2:3], off offset:256
	global_load_dwordx4 v[158:161], v[2:3], off
	v_lshl_add_u64 v[0:1], vcc, 0, v[186:187]
	v_lshl_add_u64 v[0:1], v[0:1], 0, v[204:205]
	global_load_dwordx4 v[162:165], v[0:1], off
	v_sub_u32_e32 v0, v168, v169
	v_add_u32_e32 v231, s2, v0
	v_lshl_add_u64 v[0:1], s[74:75], 0, v[198:199]
	v_lshl_add_u64 v[0:1], v[0:1], 0, s[20:21]
	s_mov_b64 s[36:37], 0x3e804000
	v_lshl_add_u64 v[206:207], v[0:1], 0, s[36:37]
	v_lshl_add_u64 v[0:1], s[42:43], 0, v[200:201]
	v_lshl_add_u64 v[0:1], v[0:1], 0, s[24:25]
	s_mov_b64 s[36:37], 0x32878100
	v_mov_b32_e32 v32, v97
	v_mov_b32_e32 v33, v97
	v_mov_b32_e32 v46, v97
	v_mov_b32_e32 v47, v97
	v_lshl_add_u64 v[208:209], v[0:1], 0, s[36:37]
	s_add_i32 m0, s33, -5
	s_cmp_lg_u64 s[30:31], 0
	s_cselect_b32 m0, m0, 0
	s_ashr_i32 s37, m0, 19
	s_lshl_b32 s36, m0, 13
	v_lshl_add_u64 v[206:207], v[206:207], 0, s[36:37]
	s_mul_i32 m0, m0, 3
	s_ashr_i32 s37, m0, 16
	s_lshl_b32 s36, m0, 16
	v_lshl_add_u64 v[208:209], v[208:209], 0, s[36:37]
	v_mov_b32_e32 v34, v97
	v_mov_b32_e32 v35, v97
	v_mov_b32_e32 v36, v97
	v_mov_b32_e32 v37, v97
	v_mov_b32_e32 v38, v97
	v_mov_b32_e32 v39, v97
	v_mov_b32_e32 v40, v97
	v_mov_b32_e32 v41, v97
	v_mov_b32_e32 v42, v97
	v_mov_b32_e32 v43, v97
	v_mov_b32_e32 v44, v97
	v_mov_b32_e32 v45, v97
	v_mov_b64_e32 v[62:63], v[46:47]
	v_mov_b64_e32 v[16:17], v[32:33]
	v_mov_b64_e32 v[0:1], v[32:33]
	s_add_i32 s55, s2, 0xfff0001f
	v_lshl_add_u32 v205, v168, 2, s69
	v_lshl_add_u32 v203, v169, 2, s69
	s_sub_i32 s63, -4, s63
	v_mov_b32_e32 v232, 0xf149f2ca
	v_mov_b32_e32 v233, 0
	v_mov_b32_e32 v64, 0
	v_mov_b32_e32 v65, 0
	v_mov_b32_e32 v66, 0
	v_mov_b32_e32 v67, 0
	v_mov_b32_e32 v68, 0
	v_mov_b32_e32 v69, 0
	v_mov_b32_e32 v70, 0
	v_mov_b32_e32 v71, 0
	v_mov_b32_e32 v72, 0
	v_mov_b32_e32 v73, 0
	v_mov_b32_e32 v74, 0
	v_mov_b32_e32 v75, 0
	v_mov_b32_e32 v76, 0
	v_mov_b32_e32 v77, 0
	v_mov_b32_e32 v78, 0
	v_mov_b32_e32 v79, 0
	s_add_i32 s8, s33, -1
	s_cmp_lg_u64 s[30:31], 0
	s_cselect_b32 s8, s8, 0
	s_lshl_b32 s8, s8, 6
	s_sub_i32 s69, 0, s8
	v_mov_b64_e32 v[60:61], v[44:45]
	v_mov_b64_e32 v[58:59], v[42:43]
	v_mov_b64_e32 v[56:57], v[40:41]
	v_mov_b64_e32 v[54:55], v[38:39]
	v_mov_b64_e32 v[52:53], v[36:37]
	v_mov_b64_e32 v[50:51], v[34:35]
	v_mov_b64_e32 v[48:49], v[32:33]
	v_mov_b64_e32 v[18:19], v[34:35]
	v_mov_b64_e32 v[20:21], v[36:37]
	v_mov_b64_e32 v[22:23], v[38:39]
	v_mov_b64_e32 v[24:25], v[40:41]
	v_mov_b64_e32 v[26:27], v[42:43]
	v_mov_b64_e32 v[28:29], v[44:45]
	v_mov_b64_e32 v[30:31], v[46:47]
	v_mov_b64_e32 v[2:3], v[34:35]
	v_mov_b64_e32 v[4:5], v[36:37]
	v_mov_b64_e32 v[6:7], v[38:39]
	v_mov_b64_e32 v[8:9], v[40:41]
	v_mov_b64_e32 v[10:11], v[42:43]
	v_mov_b64_e32 v[12:13], v[44:45]
	v_mov_b64_e32 v[14:15], v[46:47]
	s_mov_b32 s36, 0
	s_mov_b32 s37, 0
	s_waitcnt lgkmcnt(0)
	s_barrier
.LBB0_146:
	s_mov_b32 s70, s36
	s_cmp_eq_u32 s57, 2
	s_cselect_b64 s[42:43], -1, 0
	s_xor_b64 s[74:75], s[80:81], -1
	s_or_b64 s[42:43], s[74:75], s[42:43]
	s_and_b64 vcc, exec, s[42:43]
	s_cbranch_vccnz .LBB0_148
	s_setprio 1
	v_lshl_add_u32 v210, s37, 14, v218
	ds_read_b64_tr_b16 v[80:81], v210 offset:0
	ds_read_b64_tr_b16 v[82:83], v210 offset:0x800
	ds_read_b64_tr_b16 v[84:85], v210 offset:0x1000
	ds_read_b64_tr_b16 v[86:87], v210 offset:0x1800
	ds_read_b64_tr_b16 v[88:89], v210 offset:0x2000
	ds_read_b64_tr_b16 v[90:91], v210 offset:0x2800
	ds_read_b64_tr_b16 v[92:93], v210 offset:0x3000
	ds_read_b64_tr_b16 v[94:95], v210 offset:0x3800
	s_waitcnt lgkmcnt(0)
	s_nop 0
	v_mfma_f32_32x32x16_bf16 v[32:47], v[76:79], v[80:83], v[32:47]
	ds_read_b64_tr_b16 v[80:81], v210 offset:0x200
	ds_read_b64_tr_b16 v[82:83], v210 offset:0xa00
	v_mfma_f32_32x32x16_bf16 v[32:47], v[72:75], v[84:87], v[32:47]
	ds_read_b64_tr_b16 v[84:85], v210 offset:0x1200
	ds_read_b64_tr_b16 v[86:87], v210 offset:0x1a00
	v_mfma_f32_32x32x16_bf16 v[32:47], v[68:71], v[88:91], v[32:47]
	ds_read_b64_tr_b16 v[88:89], v210 offset:0x2200
	ds_read_b64_tr_b16 v[90:91], v210 offset:0x2a00
	v_mfma_f32_32x32x16_bf16 v[32:47], v[64:67], v[92:95], v[32:47]
	ds_read_b64_tr_b16 v[92:93], v210 offset:0x3200
	ds_read_b64_tr_b16 v[94:95], v210 offset:0x3a00
	s_waitcnt lgkmcnt(0)
	v_mfma_f32_32x32x16_bf16 v[48:63], v[76:79], v[80:83], v[48:63]
	ds_read_b64_tr_b16 v[80:81], v210 offset:0x400
	ds_read_b64_tr_b16 v[82:83], v210 offset:0xc00
	v_mfma_f32_32x32x16_bf16 v[48:63], v[72:75], v[84:87], v[48:63]
	ds_read_b64_tr_b16 v[84:85], v210 offset:0x1400
	ds_read_b64_tr_b16 v[86:87], v210 offset:0x1c00
	v_mfma_f32_32x32x16_bf16 v[48:63], v[68:71], v[88:91], v[48:63]
	ds_read_b64_tr_b16 v[88:89], v210 offset:0x2400
	ds_read_b64_tr_b16 v[90:91], v210 offset:0x2c00
	v_mfma_f32_32x32x16_bf16 v[48:63], v[64:67], v[92:95], v[48:63]
	ds_read_b64_tr_b16 v[92:93], v210 offset:0x3400
	ds_read_b64_tr_b16 v[94:95], v210 offset:0x3c00
	s_waitcnt lgkmcnt(0)
	v_mfma_f32_32x32x16_bf16 v[16:31], v[76:79], v[80:83], v[16:31]
	ds_read_b64_tr_b16 v[80:81], v210 offset:0x600
	ds_read_b64_tr_b16 v[82:83], v210 offset:0xe00
	v_mfma_f32_32x32x16_bf16 v[16:31], v[72:75], v[84:87], v[16:31]
	ds_read_b64_tr_b16 v[84:85], v210 offset:0x1600
	ds_read_b64_tr_b16 v[86:87], v210 offset:0x1e00
	v_mfma_f32_32x32x16_bf16 v[16:31], v[68:71], v[88:91], v[16:31]
	ds_read_b64_tr_b16 v[88:89], v210 offset:0x2600
	ds_read_b64_tr_b16 v[90:91], v210 offset:0x2e00
	v_mfma_f32_32x32x16_bf16 v[16:31], v[64:67], v[92:95], v[16:31]
	ds_read_b64_tr_b16 v[92:93], v210 offset:0x3600
	ds_read_b64_tr_b16 v[94:95], v210 offset:0x3e00
	s_waitcnt lgkmcnt(0)
	v_mfma_f32_32x32x16_bf16 v[0:15], v[76:79], v[80:83], v[0:15]
	v_mfma_f32_32x32x16_bf16 v[0:15], v[72:75], v[84:87], v[0:15]
	v_mfma_f32_32x32x16_bf16 v[0:15], v[68:71], v[88:91], v[0:15]
	v_mfma_f32_32x32x16_bf16 v[0:15], v[64:67], v[92:95], v[0:15]
	s_setprio 0

.LBB0_159:
	s_add_i32 s57, s57, 1
	v_add_f32_e32 v80, v80, v81
	s_ashr_i32 m0, s100, 7
	s_sub_i32 s69, s69, m0
	s_add_i32 s8, s8, m0
	s_add_i32 s37, s63, s57
	s_mul_i32 s42, s100, 24
	s_mov_b32 s43, s101
	v_fmac_f32_e32 v80, v233, v234
	v_lshl_add_u64 v[206:207], v[206:207], 0, s[100:101]
	s_cmp_eq_u32 s37, 2
	v_lshl_add_u64 v[208:209], v[208:209], 0, s[42:43]
	s_waitcnt lgkmcnt(0)
	s_barrier
	s_cbranch_scc1 .LBB0_161
	s_mov_b32 s37, s70
	v_mov_b32_e32 v233, v80
	s_branch .LBB0_146

	.amdhsa_kernel _Z8yoco_fwd4Args
		.amdhsa_group_segment_fixed_size 0
		.amdhsa_private_segment_fixed_size 0
		.amdhsa_kernarg_size 480
		.amdhsa_user_sgpr_count 2
		.amdhsa_user_sgpr_dispatch_ptr 0
		.amdhsa_user_sgpr_queue_ptr 0
		.amdhsa_user_sgpr_kernarg_segment_ptr 1
		.amdhsa_user_sgpr_dispatch_id 0
		.amdhsa_user_sgpr_kernarg_preload_length 0
		.amdhsa_user_sgpr_kernarg_preload_offset 0
		.amdhsa_user_sgpr_private_segment_size 0
		.amdhsa_uses_dynamic_stack 0
		.amdhsa_enable_private_segment 0
		.amdhsa_system_sgpr_workgroup_id_x 1
		.amdhsa_system_sgpr_workgroup_id_y 0
		.amdhsa_system_sgpr_workgroup_id_z 0
		.amdhsa_system_sgpr_workgroup_info 0
		.amdhsa_system_vgpr_workitem_id 2
		.amdhsa_next_free_vgpr 256
		.amdhsa_next_free_sgpr 102
		.amdhsa_accum_offset 256
		.amdhsa_reserve_vcc 1
		.amdhsa_float_round_mode_32 0
		.amdhsa_float_round_mode_16_64 0
		.amdhsa_float_denorm_mode_32 3
		.amdhsa_float_denorm_mode_16_64 3
		.amdhsa_dx10_clamp 1
		.amdhsa_ieee_mode 1
		.amdhsa_fp16_overflow 0
		.amdhsa_tg_split 0
		.amdhsa_exception_fp_ieee_invalid_op 0
		.amdhsa_exception_fp_denorm_src 0
		.amdhsa_exception_fp_ieee_div_zero 0
		.amdhsa_exception_fp_ieee_overflow 0
		.amdhsa_exception_fp_ieee_underflow 0
		.amdhsa_exception_fp_ieee_inexact 0
		.amdhsa_exception_int_div_zero 0
	.end_amdhsa_kernel

amdhsa.kernels:
  - .agpr_count:     0
    .args:
      - .offset:         0
        .size:           224
        .value_kind:     by_value
      - .offset:         224
        .size:           4
        .value_kind:     hidden_block_count_x
      - .offset:         228
        .size:           4
        .value_kind:     hidden_block_count_y
      - .offset:         232
        .size:           4
        .value_kind:     hidden_block_count_z
      - .offset:         236
        .size:           2
        .value_kind:     hidden_group_size_x
      - .offset:         238
        .size:           2
        .value_kind:     hidden_group_size_y
      - .offset:         240
        .size:           2
        .value_kind:     hidden_group_size_z
      - .offset:         242
        .size:           2
        .value_kind:     hidden_remainder_x
      - .offset:         244
        .size:           2
        .value_kind:     hidden_remainder_y
      - .offset:         246
        .size:           2
        .value_kind:     hidden_remainder_z
      - .offset:         264
        .size:           8
        .value_kind:     hidden_global_offset_x
      - .offset:         272
        .size:           8
        .value_kind:     hidden_global_offset_y
      - .offset:         280
        .size:           8
        .value_kind:     hidden_global_offset_z
      - .offset:         288
        .size:           2
        .value_kind:     hidden_grid_dims
      - .offset:         312
        .size:           8
        .value_kind:     hidden_multigrid_sync_arg
      - .offset:         344
        .size:           4
        .value_kind:     hidden_dynamic_lds_size
    .group_segment_fixed_size: 0
    .kernarg_segment_align: 8
    .kernarg_segment_size: 480
    .language:       OpenCL C
    .language_version:
      - 2
      - 0
    .max_flat_workgroup_size: 512
    .name:           _Z8yoco_fwd4Args
    .private_segment_fixed_size: 0
    .sgpr_count:     108
    .sgpr_spill_count: 99
    .symbol:         _Z8yoco_fwd4Args.kd
    .uniform_work_group_size: 1
    .uses_dynamic_stack: false
    .vgpr_count:     256
    .vgpr_spill_count: 0
    .wavefront_size: 64
